# P0 cooperative-groups sync replaced by two-level counter barrier; last full barrier site converted to group barrier; NSA compress stage-2: weight staging and partial-sum loads issued together instead
# speedup vs baseline: 1.0614x; 1.0115x over previous
.LBB0_411:
	v_lshrrev_b32_e32 v1, 20, v0
	v_lshrrev_b32_e32 v0, 10, v0
	v_or_b32_e32 v0, v0, v1
	s_movk_i32 s0, 0x3ff
	v_and_or_b32 v0, v0, s0, v196
	v_cmp_eq_u32_e32 vcc, 0, v0
	s_waitcnt lgkmcnt(0)
	s_barrier
	s_and_saveexec_b64 s[0:1], vcc
	s_xor_b64 s[4:5], exec, s[0:1]
	s_cbranch_execz .LBB0_421
	buffer_wbl2 sc1
	s_load_dwordx2 s[6:7], s[68:69], 0xb8
	v_readlane_b32 s0, v250, 63
	v_readlane_b32 s10, v250, 59
	v_mov_b32_e32 v0, 0
	v_mov_b32_e32 v1, 1
	s_mov_b32 s1, 0
	s_waitcnt vmcnt(0) lgkmcnt(0)
	s_add_u32 s8, s6, 0x123e00
	s_addc_u32 s9, s7, 0
	s_add_u32 s6, s6, s0
	s_addc_u32 s7, s7, 0
	global_atomic_add v2, v0, v1, s[6:7] offset:64 sc0
	s_waitcnt vmcnt(0)
	v_readfirstlane_b32 s0, v2
	s_add_u32 s0, s0, 1
	s_cmp_lg_u32 s0, s10
	s_cbranch_scc1 .Lp0_spin
	global_atomic_add v0, v1, s[8:9]
.Lp0_spin:
	global_load_dword v2, v0, s[8:9] sc1
	s_add_u32 s1, s1, 1
	s_waitcnt vmcnt(0)
	v_cmp_gt_u32_e32 vcc, 8, v2
	s_cbranch_vccz .Lp0_rel
	s_cmp_lt_u32 s1, 0x200000
	s_cbranch_scc0 .Lp0_rel
	s_sleep 1
	s_branch .Lp0_spin
.Lp0_rel:
	buffer_inv sc1
	s_waitcnt vmcnt(0)

.LBB0_1020:
	s_or_b64 exec, exec, s[2:3]
	s_mov_b64 s[0:1], s[68:69]
	s_waitcnt lgkmcnt(0)
	s_barrier
	s_load_dwordx2 s[4:5], s[0:1], 0xb8
	s_mov_b64 s[0:1], s[68:69]
	s_load_dwordx2 s[6:7], s[0:1], 0xb8
	s_mov_b64 s[12:13], s[68:69]
	s_mov_b64 s[0:1], s[68:69]
	s_load_dwordx2 s[8:9], s[0:1], 0xb8
	s_mov_b64 s[0:1], s[68:69]
	s_load_dwordx2 s[10:11], s[0:1], 0xb8
	v_mov_b32_e32 v4, v196
	v_mov_b32_e32 v5, v196
	v_mov_b32_e32 v0, v196
	s_nop 0
	v_cmp_gt_i32_e32 vcc, s67, v0
	s_and_saveexec_b64 s[2:3], vcc
	s_mov_b64 s[20:21], 0x800
	s_cbranch_execz .LBB0_1028
	s_load_dwordx2 s[12:13], s[12:13], 0x98
	v_readlane_b32 s0, v251, 63
	v_lshlrev_b32_e32 v1, 4, v0
	s_waitcnt lgkmcnt(0)
	s_add_u32 s16, s12, s0
	s_addc_u32 s17, s13, 0
	global_load_dwordx4 v[6:9], v1, s[16:17]
	v_add_u32_e32 v2, 0x2000, v1
	global_load_dwordx4 v[10:13], v2, s[16:17]
	v_add_u32_e32 v3, 0x4000, v1
	global_load_dwordx4 v[14:17], v3, s[16:17]
	v_add_u32_e32 v38, 0x6000, v1
	global_load_dwordx4 v[18:21], v38, s[16:17]
	v_add_u32_e32 v39, 0x8000, v1
	global_load_dwordx4 v[22:25], v39, s[16:17]
	v_add_u32_e32 v2, 0xa000, v1
	global_load_dwordx4 v[26:29], v2, s[16:17]
	v_add_u32_e32 v3, 0xc000, v1
	global_load_dwordx4 v[30:33], v3, s[16:17]
	v_add_u32_e32 v38, 0xe000, v1
	global_load_dwordx4 v[34:37], v38, s[16:17]
	s_waitcnt vmcnt(7)
	ds_write_b128 v1, v[6:9]
	s_waitcnt vmcnt(6)
	ds_write_b128 v1, v[10:13] offset:8192
	s_waitcnt vmcnt(5)
	ds_write_b128 v1, v[14:17] offset:16384
	s_waitcnt vmcnt(4)
	ds_write_b128 v1, v[18:21] offset:24576
	s_waitcnt vmcnt(3)
	ds_write_b128 v1, v[22:25] offset:32768
	s_waitcnt vmcnt(2)
	ds_write_b128 v1, v[26:29] offset:40960
	s_waitcnt vmcnt(1)
	ds_write_b128 v1, v[30:33] offset:49152
	s_waitcnt vmcnt(0)
	ds_write_b128 v1, v[34:37] offset:57344

.LBB0_1031:
	v_ashrrev_i32_e32 v10, 11, v1
	v_ashrrev_i32_e32 v11, 31, v10
	v_lshlrev_b64 v[12:13], 23, v[10:11]
	s_movk_i32 s0, 0xf800
	v_lshl_add_u64 v[34:35], s[4:5], 0, v[12:13]
	v_and_or_b32 v12, v1, s0, v0
	v_ashrrev_i32_e32 v13, 31, v12
	v_lshl_add_u64 v[36:37], v[12:13], 2, s[6:7]
	s_movk_i32 s0, 0x1000
	v_add_co_u32_e32 v38, vcc, s0, v36
	v_and_b32_e32 v4, 0x7ff, v1
	s_nop 0
	v_addc_co_u32_e32 v39, vcc, 0, v37, vcc
	v_lshlrev_b32_e32 v92, 9, v4
	v_lshl_add_u64 v[34:35], v[34:35], 0, v[92:93]
	v_mov_b32_e32 v3, v93
	v_lshl_add_u64 v[34:35], v[34:35], 0, v[2:3]
	s_mov_b32 s0, 0x100000
	s_mov_b32 s1, 0
	global_load_dword v10, v[36:37], off
	global_load_dword v11, v[36:37], off offset:512
	global_load_dword v12, v[36:37], off offset:1024
	global_load_dword v13, v[36:37], off offset:1536
	global_load_dword v14, v[36:37], off offset:2048
	global_load_dword v15, v[36:37], off offset:2560
	global_load_dword v16, v[36:37], off offset:3072
	global_load_dword v17, v[36:37], off offset:3584
	global_load_dword v18, v[38:39], off
	global_load_dword v19, v[38:39], off offset:512
	global_load_dword v20, v[38:39], off offset:1024
	global_load_dword v21, v[38:39], off offset:1536
	global_load_dword v22, v[38:39], off offset:2048
	global_load_dword v23, v[38:39], off offset:2560
	global_load_dword v24, v[38:39], off offset:3072
	global_load_dword v25, v[38:39], off offset:3584
	v_mov_b32_e32 v4, v34
	v_mov_b32_e32 v5, v35
	global_load_dword v26, v[4:5], off
	v_lshl_add_u64 v[4:5], v[4:5], 0, s[0:1]
	global_load_dword v27, v[4:5], off
	v_lshl_add_u64 v[4:5], v[4:5], 0, s[0:1]
	global_load_dword v28, v[4:5], off
	v_lshl_add_u64 v[4:5], v[4:5], 0, s[0:1]
	global_load_dword v29, v[4:5], off
	v_lshl_add_u64 v[4:5], v[4:5], 0, s[0:1]
	global_load_dword v30, v[4:5], off
	v_lshl_add_u64 v[4:5], v[4:5], 0, s[0:1]
	global_load_dword v31, v[4:5], off
	v_lshl_add_u64 v[4:5], v[4:5], 0, s[0:1]
	global_load_dword v32, v[4:5], off
	v_lshl_add_u64 v[4:5], v[4:5], 0, s[0:1]
	global_load_dword v33, v[4:5], off
	s_waitcnt vmcnt(0)
	v_add_f32_e32 v3, 0, v10
	v_add_f32_e32 v3, v3, v11
	v_add_f32_e32 v3, v3, v12
	v_add_f32_e32 v3, v3, v13
	v_add_f32_e32 v3, v3, v14
	v_add_f32_e32 v3, v3, v15
	v_add_f32_e32 v3, v3, v16
	v_add_f32_e32 v3, v3, v17
	v_add_f32_e32 v3, v3, v18
	v_add_f32_e32 v3, v3, v19
	v_add_f32_e32 v3, v3, v20
	v_add_f32_e32 v3, v3, v21
	v_add_f32_e32 v3, v3, v22
	v_add_f32_e32 v3, v3, v23
	v_add_f32_e32 v3, v3, v24
	v_add_f32_e32 v3, v3, v25
	v_add_f32_e32 v3, v3, v26
	v_add_f32_e32 v3, v3, v27
	v_add_f32_e32 v3, v3, v28
	v_add_f32_e32 v3, v3, v29
	v_add_f32_e32 v3, v3, v30
	v_add_f32_e32 v3, v3, v31
	v_add_f32_e32 v3, v3, v32
	v_add_f32_e32 v3, v3, v33
	v_mul_f32_e32 v10, 0xbfb8aa3b, v3
	v_exp_f32_e32 v10, v10
	s_nop 0
	v_add_f32_e32 v10, 1.0, v10
	v_rcp_f32_e32 v10, v10
	s_nop 0
	v_mul_f32_e32 v3, v3, v10
	global_load_dword v10, v[36:37], off offset:256
	global_load_dword v11, v[36:37], off offset:768
	global_load_dword v12, v[36:37], off offset:1280
	global_load_dword v13, v[36:37], off offset:1792
	global_load_dword v14, v[36:37], off offset:2304
	global_load_dword v15, v[36:37], off offset:2816
	global_load_dword v16, v[36:37], off offset:3328
	global_load_dword v17, v[36:37], off offset:3840
	global_load_dword v18, v[38:39], off offset:256
	global_load_dword v19, v[38:39], off offset:768
	global_load_dword v20, v[38:39], off offset:1280
	global_load_dword v21, v[38:39], off offset:1792
	global_load_dword v22, v[38:39], off offset:2304
	global_load_dword v23, v[38:39], off offset:2816
	global_load_dword v24, v[38:39], off offset:3328
	global_load_dword v25, v[38:39], off offset:3840
	v_mov_b32_e32 v4, v34
	v_mov_b32_e32 v5, v35
	global_load_dword v26, v[4:5], off offset:256
	v_lshl_add_u64 v[4:5], v[4:5], 0, s[0:1]
	global_load_dword v27, v[4:5], off offset:256
	v_lshl_add_u64 v[4:5], v[4:5], 0, s[0:1]
	global_load_dword v28, v[4:5], off offset:256
	v_lshl_add_u64 v[4:5], v[4:5], 0, s[0:1]
	global_load_dword v29, v[4:5], off offset:256
	v_lshl_add_u64 v[4:5], v[4:5], 0, s[0:1]
	global_load_dword v30, v[4:5], off offset:256
	v_lshl_add_u64 v[4:5], v[4:5], 0, s[0:1]
	global_load_dword v31, v[4:5], off offset:256
	v_lshl_add_u64 v[4:5], v[4:5], 0, s[0:1]
	global_load_dword v32, v[4:5], off offset:256
	v_lshl_add_u64 v[4:5], v[4:5], 0, s[0:1]
	global_load_dword v33, v[4:5], off offset:256
	v_mov_b32_e32 v35, v3
	v_ashrrev_i32_e32 v4, 11, v1
	v_lshlrev_b32_e32 v4, 15, v4
	v_add_u32_e32 v34, v6, v4
	v_and_b32_e32 v4, 0x7ff, v1
	v_mov_b32_e32 v5, 0
	s_mov_b32 s0, 0
.LBB0_1032:
	v_add_u32_e32 v38, s0, v8
	ds_bpermute_b32 v39, v38, v35
	ds_read2st64_b32 v[36:37], v34 offset1:1
	s_add_i32 s0, s0, 32
	s_cmpk_eq_i32 s0, 0x100
	s_waitcnt lgkmcnt(0)
	v_fmac_f32_e32 v5, v36, v39
	ds_bpermute_b32 v36, v38, v35 offset:4
	ds_bpermute_b32 v39, v38, v35 offset:8
	s_waitcnt lgkmcnt(1)
	v_fmac_f32_e32 v5, v37, v36
	ds_read2st64_b32 v[36:37], v34 offset0:2 offset1:3
	s_waitcnt lgkmcnt(0)
	v_fmac_f32_e32 v5, v36, v39
	ds_bpermute_b32 v36, v38, v35 offset:12
	ds_bpermute_b32 v39, v38, v35 offset:16
	s_waitcnt lgkmcnt(1)
	v_fmac_f32_e32 v5, v37, v36
	ds_read2st64_b32 v[36:37], v34 offset0:4 offset1:5
	s_waitcnt lgkmcnt(0)
	v_fmac_f32_e32 v5, v36, v39
	ds_bpermute_b32 v36, v38, v35 offset:20
	ds_bpermute_b32 v39, v38, v35 offset:24
	s_waitcnt lgkmcnt(1)
	v_fmac_f32_e32 v5, v37, v36
	ds_read2st64_b32 v[36:37], v34 offset0:6 offset1:7
	v_add_u32_e32 v34, 0x800, v34
	s_waitcnt lgkmcnt(0)
	v_fmac_f32_e32 v5, v36, v39
	ds_bpermute_b32 v36, v38, v35 offset:28
	s_waitcnt lgkmcnt(0)
	v_fmac_f32_e32 v5, v37, v36
	s_cbranch_scc0 .LBB0_1032
	s_waitcnt vmcnt(0)
	v_add_f32_e32 v3, 0, v10
	v_add_f32_e32 v3, v3, v11
	v_add_f32_e32 v3, v3, v12
	v_add_f32_e32 v3, v3, v13
	v_add_f32_e32 v3, v3, v14
	v_add_f32_e32 v3, v3, v15
	v_add_f32_e32 v3, v3, v16
	v_add_f32_e32 v3, v3, v17
	v_add_f32_e32 v3, v3, v18
	v_add_f32_e32 v3, v3, v19
	v_add_f32_e32 v3, v3, v20
	v_add_f32_e32 v3, v3, v21
	v_add_f32_e32 v3, v3, v22
	v_add_f32_e32 v3, v3, v23
	v_add_f32_e32 v3, v3, v24
	v_add_f32_e32 v3, v3, v25
	v_add_f32_e32 v3, v3, v26
	v_add_f32_e32 v3, v3, v27
	v_add_f32_e32 v3, v3, v28
	v_add_f32_e32 v3, v3, v29
	v_add_f32_e32 v3, v3, v30
	v_add_f32_e32 v3, v3, v31
	v_add_f32_e32 v3, v3, v32
	v_add_f32_e32 v3, v3, v33
	v_mul_f32_e32 v10, 0xbfb8aa3b, v3
	v_exp_f32_e32 v10, v10
	s_nop 0
	v_add_f32_e32 v10, 1.0, v10
	v_rcp_f32_e32 v10, v10
	s_nop 0
	v_mul_f32_e32 v10, v3, v10
	v_ashrrev_i32_e32 v3, 11, v1
	v_lshlrev_b32_e32 v3, 15, v3
	v_add_u32_e32 v3, v9, v3
	s_mov_b32 s0, 0

.Lgb13_long:
	s_getpc_b64 s[98:99]

.LBB0_2102:
	v_writelane_b32 v250, s8, 44
	v_writelane_b32 v250, s9, 45
	v_writelane_b32 v250, s10, 46
	v_writelane_b32 v250, s11, 47
	v_writelane_b32 v250, s12, 48
	v_writelane_b32 v250, s13, 49
	v_writelane_b32 v250, s14, 50
	v_writelane_b32 v250, s15, 51
	s_load_dwordx2 s[8:9], s[68:69], 0xb8
	v_readfirstlane_b32 s12, v0
	v_readfirstlane_b32 s13, v1
	v_readlane_b32 s10, v250, 63
	v_readlane_b32 s11, v250, 61
	v_readlane_b32 s14, v250, 59
	v_mov_b32_e32 v0, 0
	s_mov_b32 s15, 0
	s_waitcnt lgkmcnt(0)
	s_add_u32 s8, s8, s10
	s_addc_u32 s9, s9, 0
	s_cmp_lg_u32 s11, 0
	s_cbranch_scc1 .Lgb13_known
	global_load_dword v1, v0, s[8:9] offset:128 sc1
	s_waitcnt vmcnt(0)
	v_readfirstlane_b32 s10, v1
	s_sub_u32 s11, s10, 1
	s_and_b32 s11, s11, s10
	s_cmp_eq_u32 s11, 0
	s_cselect_b32 s11, 2, 1
	s_cmp_eq_u32 s10, 0
	s_cselect_b32 s11, 1, s11
	v_writelane_b32 v250, s11, 61
	s_nop 0

.Lgb13_done:
	v_mov_b32_e32 v0, s12
	v_mov_b32_e32 v1, s13
	v_readlane_b32 s8, v250, 44
	v_readlane_b32 s9, v250, 45
	v_readlane_b32 s10, v250, 46
	v_readlane_b32 s11, v250, 47
	v_readlane_b32 s12, v250, 48
	v_readlane_b32 s13, v250, 49
	v_readlane_b32 s14, v250, 50
	v_readlane_b32 s15, v250, 51
	s_branch .Lgb13_long
.LBB0_2152:
	s_mov_b64 s[2:3], s[68:69]
	s_mov_b64 s[4:5], s[68:69]
	v_mov_b32_e32 v0, v196
	v_readlane_b32 s6, v251, 20
	v_ashrrev_i32_e32 v18, 6, v196
	v_readlane_b32 s7, v251, 21
	v_add_u32_e32 v22, s6, v18
	v_cmp_gt_i32_e32 vcc, s73, v22
	s_and_saveexec_b64 s[0:1], vcc
	s_cbranch_execz .LBB0_2155
	s_load_dwordx2 s[0:1], s[4:5], 0x30
	v_and_b32_e32 v0, 63, v0
	v_lshlrev_b32_e32 v16, 4, v0
	v_cmp_lt_i32_e32 vcc, v204, v198
	v_ashrrev_i32_e32 v19, 31, v18
	s_waitcnt lgkmcnt(0)
	global_load_dwordx4 v[0:3], v16, s[0:1]
	global_load_dwordx4 v[4:7], v16, s[0:1] offset:1024
	global_load_dwordx4 v[8:11], v16, s[0:1] offset:2048
	global_load_dwordx4 v[12:15], v16, s[0:1] offset:3072
	v_cndmask_b32_e32 v17, v197, v204, vcc
	v_cmp_lt_i32_e32 vcc, v205, v198
	s_load_dwordx2 s[0:1], s[2:3], 0xb8
	s_load_dwordx2 s[4:5], s[68:69], 0xb0
	v_lshlrev_b32_e32 v23, 2, v17
	v_cndmask_b32_e32 v17, v197, v205, vcc
	v_cmp_lt_i32_e32 vcc, v203, v198
	v_lshlrev_b32_e32 v24, 2, v17
	v_lshl_add_u64 v[18:19], s[6:7], 0, v[18:19]
	v_cndmask_b32_e32 v17, v197, v203, vcc
	v_cmp_lt_i32_e32 vcc, v202, v198
	v_lshlrev_b32_e32 v25, 2, v17
	v_lshlrev_b64 v[20:21], 12, v[18:19]
	v_cndmask_b32_e32 v17, v197, v202, vcc
	v_cmp_lt_i32_e32 vcc, v201, v198
	v_lshlrev_b32_e32 v26, 2, v17
	s_waitcnt lgkmcnt(0)
	v_lshl_add_u64 v[18:19], s[0:1], 0, v[20:21]
	v_cndmask_b32_e32 v17, v197, v201, vcc
	v_cmp_lt_i32_e32 vcc, v199, v198
	v_lshlrev_b32_e32 v27, 2, v17
	s_mov_b64 s[0:1], 0xa46c800
	v_cndmask_b32_e32 v17, v197, v199, vcc
	v_lshlrev_b32_e32 v28, 2, v17
	v_mov_b32_e32 v17, 0
	v_lshl_add_u64 v[18:19], v[18:19], 0, s[0:1]
	v_lshl_add_u64 v[20:21], s[4:5], 0, v[20:21]
	s_mov_b64 s[0:1], 0
	v_mov_b32_e32 v29, 0x358637bd
	s_mov_b32 s2, 0x800000
